# retention cross term software-pipelined, second sitting
# speedup vs baseline: 1.0482x; 1.0011x over previous
; __device__ __forceinline__ unsigned cvt_pk_bf16(float lo, float hi) { const bf16x2_cv v = __builtin_convertvector((f32x2_cv){lo, hi}, bf16x2_cv); return __builtin_bit_cast(unsigned, v); }
; #define LAS __attribute__((address_space(3)))
; __device__ __forceinline__ void retention_fused(const Params& p, LAS unsigned char* lds, int unit) {
;     ...
; #pragma unroll
;         for (int mt = 0; mt < 2; ++mt)
; #pragma unroll
;             for (int nt = 0; nt < 4; ++nt) { u32x2 w; w.x = cvt_pk_bf16(S[mt][nt][0], S[mt][nt][1]); w.y = cvt_pk_bf16(S[mt][nt][2], S[mt][nt][3]);
;                 *(LAS u32x2*)(St + (nt * 16 + fr) * ST_STRIDE + (32 * wid + 16 * mt + fq * 4) * 2) = w; }
; #pragma unroll
;         for (int i = 0; i < 8; ++i) { const int id = tid + i * NTHREADS, row = id >> 5, cc = id & 31; *(LAS u32x4*)(Ks + row * KS_STRIDE + cc * 16) = *(const u32x4*)(Kg + (size_t)(c * 128 + row) * D + cc * 8); }
; #pragma unroll
;         for (int i = 0; i < 2; ++i) { const int id = tid + i * NTHREADS, row = id >> 3, cc = id & 7;
;             const u32x4 v = *(const u32x4*)(Vg + (size_t)(c * 128 + row) * VD + cc * 8);
;             *(LAS u32x4*)(Vs + row * VS_STRIDE + cc * 16) = v;
;             const float sw = __builtin_amdgcn_exp2f((float)(127 - row) * log2g);
;             u32x4 w; w.x = cvt_pk_bf16(bflo(v.x) * sw, bfhi(v.x) * sw); w.y = cvt_pk_bf16(bflo(v.y) * sw, bfhi(v.y) * sw); w.z = cvt_pk_bf16(bflo(v.z) * sw, bfhi(v.z) * sw); w.w = cvt_pk_bf16(bflo(v.w) * sw, bfhi(v.w) * sw);
;             *(LAS u32x4*)(Vw + row * VS_STRIDE + cc * 16) = w; }
;         bf16x8 qf[8];
; #pragma unroll
;         for (int ks = 0; ks < 8; ++ks) qf[ks] = *(const bf16x8*)(Qg + (size_t)(c * 128 + 16 * wid + fr) * D + ks * 32 + fq * 8);
;         __syncthreads();
.LBB0_1046:
	s_lshl_b32 s23, s57, 17
	v_or_b32_e32 v50, s23, v191
	v_or_b32_e32 v52, s23, v192
	v_or_b32_e32 v58, s23, v193
	v_or_b32_e32 v60, s23, v194
	v_lshlrev_b32_e32 v50, 1, v50
	v_mov_b32_e32 v51, v119
	v_lshlrev_b32_e32 v52, 1, v52
	v_mov_b32_e32 v53, v119
	v_lshlrev_b32_e32 v58, 1, v58
	v_mov_b32_e32 v59, v119
	v_lshlrev_b32_e32 v60, 1, v60
	v_mov_b32_e32 v61, v119
	v_lshl_add_u64 v[50:51], v[120:121], 0, v[50:51]
	v_lshl_add_u64 v[54:55], v[120:121], 0, v[52:53]
	v_lshl_add_u64 v[58:59], v[120:121], 0, v[58:59]
	v_lshl_add_u64 v[62:63], v[120:121], 0, v[60:61]
	global_load_dwordx4 v[50:53], v[50:51], off
	s_nop 0
	global_load_dwordx4 v[54:57], v[54:55], off
	s_nop 0
	global_load_dwordx4 v[58:61], v[58:59], off
	s_nop 0
	global_load_dwordx4 v[62:65], v[62:63], off
	v_or_b32_e32 v66, s23, v195
	v_or_b32_e32 v68, s23, v196
	v_lshlrev_b32_e32 v66, 1, v66
	v_mov_b32_e32 v67, v119
	v_lshlrev_b32_e32 v68, 1, v68
	v_mov_b32_e32 v69, v119
	v_or_b32_e32 v74, s23, v197
	v_lshl_add_u64 v[66:67], v[120:121], 0, v[66:67]
	v_lshl_add_u64 v[70:71], v[120:121], 0, v[68:69]
	v_lshlrev_b32_e32 v74, 1, v74
	v_mov_b32_e32 v75, v119
	v_add_lshl_u32 v76, s23, v198, 1
	v_mov_b32_e32 v77, v119
	global_load_dwordx4 v[66:69], v[66:67], off
	s_nop 0
	global_load_dwordx4 v[70:73], v[70:71], off
	v_lshl_add_u64 v[74:75], v[120:121], 0, v[74:75]
	v_lshl_add_u64 v[78:79], v[120:121], 0, v[76:77]
	global_load_dwordx4 v[74:77], v[74:75], off
	s_nop 0
	global_load_dwordx4 v[78:81], v[78:79], off
	s_lshl_b32 s23, s57, 18
	v_or_b32_e32 v82, s23, v199
	v_lshlrev_b32_e32 v82, 1, v82
	v_mov_b32_e32 v83, v119
	v_lshl_add_u64 v[82:83], v[122:123], 0, v[82:83]
	global_load_dwordx4 v[178:181], v[82:83], off
	v_add_lshl_u32 v82, s23, v201, 1
	v_mov_b32_e32 v83, v119
	v_lshl_add_u64 v[82:83], v[122:123], 0, v[82:83]
	global_load_dwordx4 v[222:225], v[82:83], off
	s_lshl_b32 s23, s57, 7
	v_mov_b32_e32 v83, v119
	v_add_u32_e32 v82, s23, v186
	v_lshlrev_b64 v[82:83], 11, v[82:83]
	v_lshl_add_u64 v[110:111], v[124:125], 0, v[82:83]
	global_load_dwordx4 v[82:85], v[110:111], off
	global_load_dwordx4 v[86:89], v[110:111], off offset:64
	global_load_dwordx4 v[90:93], v[110:111], off offset:128
	global_load_dwordx4 v[94:97], v[110:111], off offset:192
	global_load_dwordx4 v[98:101], v[110:111], off offset:256
	v_cvt_pk_bf16_f32 v102, v30, v31
	v_cvt_pk_bf16_f32 v103, v32, v33
	v_cvt_pk_bf16_f32 v112, v2, v3
	v_cvt_pk_bf16_f32 v113, v4, v5
	v_cvt_pk_bf16_f32 v104, v18, v19
	v_cvt_pk_bf16_f32 v105, v20, v21
	v_cvt_pk_bf16_f32 v106, v22, v23
	v_cvt_pk_bf16_f32 v107, v24, v25
	v_cvt_pk_bf16_f32 v226, v6, v7
	v_cvt_pk_bf16_f32 v227, v8, v9
	v_add_u32_e32 v117, 0x2000, v208
	v_cvt_pk_bf16_f32 v228, v10, v11
	v_cvt_pk_bf16_f32 v229, v12, v13
	v_add_u32_e32 v161, 0x4000, v208
	ds_write2_b64 v208, v[102:103], v[112:113] offset1:4
	ds_write2_b64 v117, v[104:105], v[226:227] offset0:32 offset1:36
	ds_write2_b64 v161, v[106:107], v[228:229] offset0:64 offset1:68
	global_load_dwordx4 v[102:105], v[110:111], off offset:320
	v_cvt_pk_bf16_f32 v108, v26, v27
	v_cvt_pk_bf16_f32 v109, v28, v29
	v_cvt_pk_bf16_f32 v230, v14, v15
	v_cvt_pk_bf16_f32 v231, v16, v17
	v_add_u32_e32 v163, 0x6000, v208
	v_lshl_or_b32 v161, s58, 5, v183
	v_lshlrev_b32_e32 v182, 9, v161
	s_mov_b32 s26, 0
	v_mov_b32_e32 v117, v204
	s_mov_b32 s27, s37
	ds_write2_b64 v163, v[108:109], v[230:231] offset0:96 offset1:100
	s_waitcnt vmcnt(15)
	ds_write_b128 v209, v[50:53]
	s_waitcnt vmcnt(14)
	ds_write_b128 v210, v[54:57]
	s_waitcnt vmcnt(13)
	ds_write_b128 v209, v[58:61] offset:16896
	s_waitcnt vmcnt(12)
	ds_write_b128 v211, v[62:65]
	global_load_dwordx4 v[106:109], v[110:111], off offset:384
	s_waitcnt vmcnt(12)
	ds_write_b128 v209, v[66:69] offset:33792
	s_waitcnt vmcnt(11)
	ds_write_b128 v212, v[70:73]
	s_waitcnt vmcnt(10)
	ds_write_b128 v209, v[74:77] offset:50688
	global_load_dwordx4 v[110:113], v[110:111], off offset:448
	v_add_u32_e32 v50, v184, v200
	s_waitcnt vmcnt(10)
	ds_write_b128 v213, v[78:81]
	v_mov_b32_e32 v163, v139
	s_waitcnt vmcnt(9)
	ds_write_b128 v50, v[178:181]
	v_lshlrev_b32_e32 v50, 16, v178
	v_and_b32_e32 v51, 0xffff0000, v178
	v_lshlrev_b32_e32 v52, 16, v179
	v_and_b32_e32 v53, 0xffff0000, v179
	v_pk_mul_f32 v[50:51], v[140:141], v[50:51]
	v_pk_mul_f32 v[52:53], v[140:141], v[52:53]
	v_cvt_pk_bf16_f32 v50, v50, v51
	v_cvt_pk_bf16_f32 v51, v52, v53
	v_lshlrev_b32_e32 v52, 16, v180
	v_and_b32_e32 v53, 0xffff0000, v180
	v_lshlrev_b32_e32 v54, 16, v181
	v_and_b32_e32 v55, 0xffff0000, v181
	v_pk_mul_f32 v[52:53], v[140:141], v[52:53]
	v_pk_mul_f32 v[54:55], v[140:141], v[54:55]
	v_cvt_pk_bf16_f32 v52, v52, v53
	v_cvt_pk_bf16_f32 v53, v54, v55
	v_add_u32_e32 v54, v185, v200
	ds_write_b128 v54, v[50:53]
	v_add_u32_e32 v50, v184, v202
	s_waitcnt vmcnt(8)
	ds_write_b128 v50, v[222:225]
	v_lshlrev_b32_e32 v50, 16, v222
	v_and_b32_e32 v51, 0xffff0000, v222
	v_lshlrev_b32_e32 v52, 16, v223
	v_and_b32_e32 v53, 0xffff0000, v223
	v_pk_mul_f32 v[50:51], v[142:143], v[50:51]
	v_pk_mul_f32 v[52:53], v[142:143], v[52:53]
	v_cvt_pk_bf16_f32 v50, v50, v51
	v_cvt_pk_bf16_f32 v51, v52, v53
	v_lshlrev_b32_e32 v52, 16, v224
	v_and_b32_e32 v53, 0xffff0000, v224
	v_lshlrev_b32_e32 v54, 16, v225
	v_and_b32_e32 v55, 0xffff0000, v225
	v_pk_mul_f32 v[52:53], v[142:143], v[52:53]
	v_pk_mul_f32 v[54:55], v[142:143], v[54:55]
	v_cvt_pk_bf16_f32 v52, v52, v53
	v_cvt_pk_bf16_f32 v53, v54, v55
	v_add_u32_e32 v54, v185, v202
	ds_write_b128 v54, v[50:53]
	s_waitcnt lgkmcnt(0)
	s_barrier
; #define LAS __attribute__((address_space(3)))
; #define SAMPLE_ISSUE(hb) do { _Pragma("unroll") for (int i = 0; i < 4; ++i) s0v[i] = __builtin_nontemporal_load((const f32x4*)(S0 + (size_t)(dbase + 4 * ((hb) * 4 + i)) * 512)); } while (0)
; __device__ __forceinline__ void retention_fused(const Params& p, LAS unsigned char* lds, int unit) {
;     ...
;         SAMPLE_ISSUE(0);
;         f32x4 o[4];
; #pragma unroll
;         for (int nt = 0; nt < 4; ++nt) {
;             o[nt] = (f32x4){0.f, 0.f, 0.f, 0.f};
; #pragma unroll
;             for (int ks = 0; ks < 8; ++ks) { const bf16x8 sf = *(const LAS bf16x8*)(St + (nt * 16 + fr) * ST_STRIDE + ks * 64 + fq * 16);
;                 o[nt] = __builtin_amdgcn_mfma_f32_16x16x32_bf16(qf[ks], sf, o[nt], 0, 0, 0); }
; #pragma unroll
;             for (int r = 0; r < 4; ++r) o[nt][r] *= __builtin_amdgcn_exp2f((float)(16 * wid + fq * 4 + r + 1) * log2g);
;         }
	ds_read_b128 v[226:229], v214
	ds_read_b128 v[230:233], v214 offset:64
	ds_read_b128 v[234:237], v214 offset:128
	ds_read_b128 v[238:241], v214 offset:192
	ds_read_b128 v[242:245], v214 offset:256
	ds_read_b128 v[248:251], v214 offset:320
	ds_read_b128 v[252:255], v214 offset:384
	v_lshlrev_b32_e32 v178, 11, v161
	v_mov_b32_e32 v179, v119
	v_lshl_add_u64 v[180:181], v[164:165], 0, v[178:179]
	global_load_dwordx4 v[78:81], v[180:181], off nt
	v_add_co_u32_e32 v70, vcc, s52, v180
	s_nop 1
	v_addc_co_u32_e32 v71, vcc, 0, v181, vcc
	global_load_dwordx4 v[74:77], v[70:71], off nt
	v_add_co_u32_e32 v66, vcc, s51, v180
	s_nop 1
	v_addc_co_u32_e32 v67, vcc, 0, v181, vcc
	v_add_co_u32_e32 v68, vcc, s53, v180
	s_nop 1
	v_addc_co_u32_e32 v69, vcc, 0, v181, vcc
	global_load_dwordx4 v[70:73], v[66:67], off nt
	s_nop 0
	global_load_dwordx4 v[66:69], v[68:69], off nt
	s_waitcnt vmcnt(11) lgkmcnt(6)
	v_mfma_f32_16x16x32_bf16 v[62:65], v[82:85], v[226:229], 0
	ds_read_b128 v[222:225], v214 offset:448
	s_waitcnt vmcnt(10) lgkmcnt(6)
	v_mfma_f32_16x16x32_bf16 v[62:65], v[86:89], v[230:233], v[62:65]
	ds_read_b128 v[226:229], v214 offset:8448
	s_waitcnt vmcnt(9) lgkmcnt(6)
	v_mfma_f32_16x16x32_bf16 v[62:65], v[90:93], v[234:237], v[62:65]
	ds_read_b128 v[230:233], v214 offset:8512
	s_waitcnt vmcnt(8) lgkmcnt(6)
	v_mfma_f32_16x16x32_bf16 v[62:65], v[94:97], v[238:241], v[62:65]
	ds_read_b128 v[234:237], v214 offset:8576
	s_waitcnt vmcnt(7) lgkmcnt(6)
	v_mfma_f32_16x16x32_bf16 v[62:65], v[98:101], v[242:245], v[62:65]
	ds_read_b128 v[238:241], v214 offset:8640
	s_waitcnt vmcnt(6) lgkmcnt(6)
	v_mfma_f32_16x16x32_bf16 v[62:65], v[102:105], v[248:251], v[62:65]
	ds_read_b128 v[242:245], v214 offset:8704
	s_waitcnt vmcnt(5) lgkmcnt(6)
	v_mfma_f32_16x16x32_bf16 v[62:65], v[106:109], v[252:255], v[62:65]
	ds_read_b128 v[248:251], v214 offset:8768
	s_waitcnt vmcnt(4) lgkmcnt(6)
	v_mfma_f32_16x16x32_bf16 v[62:65], v[110:113], v[222:225], v[62:65]
	ds_read_b128 v[252:255], v214 offset:8832
	s_waitcnt lgkmcnt(6)
	v_mfma_f32_16x16x32_bf16 v[58:61], v[82:85], v[226:229], 0
	ds_read_b128 v[222:225], v214 offset:8896
	s_waitcnt lgkmcnt(6)
	v_mfma_f32_16x16x32_bf16 v[58:61], v[86:89], v[230:233], v[58:61]
	ds_read_b128 v[226:229], v214 offset:16896
	s_waitcnt lgkmcnt(6)
	v_mfma_f32_16x16x32_bf16 v[58:61], v[90:93], v[234:237], v[58:61]
	ds_read_b128 v[230:233], v214 offset:16960
	s_waitcnt lgkmcnt(6)
	v_mfma_f32_16x16x32_bf16 v[58:61], v[94:97], v[238:241], v[58:61]
	ds_read_b128 v[234:237], v214 offset:17024
	s_waitcnt lgkmcnt(6)
	v_mfma_f32_16x16x32_bf16 v[58:61], v[98:101], v[242:245], v[58:61]
	ds_read_b128 v[238:241], v214 offset:17088
	s_waitcnt lgkmcnt(6)
	v_mfma_f32_16x16x32_bf16 v[58:61], v[102:105], v[248:251], v[58:61]
	ds_read_b128 v[242:245], v214 offset:17152
	s_waitcnt lgkmcnt(6)
	v_mfma_f32_16x16x32_bf16 v[58:61], v[106:109], v[252:255], v[58:61]
	ds_read_b128 v[248:251], v214 offset:17216
	s_waitcnt lgkmcnt(6)
	v_mfma_f32_16x16x32_bf16 v[58:61], v[110:113], v[222:225], v[58:61]
	ds_read_b128 v[252:255], v214 offset:17280
	s_waitcnt lgkmcnt(6)
	v_mfma_f32_16x16x32_bf16 v[54:57], v[82:85], v[226:229], 0
	ds_read_b128 v[222:225], v214 offset:17344
	s_waitcnt lgkmcnt(6)
	v_mfma_f32_16x16x32_bf16 v[54:57], v[86:89], v[230:233], v[54:57]
	ds_read_b128 v[226:229], v214 offset:25344
	s_waitcnt lgkmcnt(6)
	v_mfma_f32_16x16x32_bf16 v[54:57], v[90:93], v[234:237], v[54:57]
	ds_read_b128 v[230:233], v214 offset:25408
	v_pk_mul_f32 v[62:63], v[144:145], v[62:63]
	s_waitcnt lgkmcnt(6)
	v_mfma_f32_16x16x32_bf16 v[54:57], v[94:97], v[238:241], v[54:57]
	ds_read_b128 v[234:237], v214 offset:25472
	s_waitcnt lgkmcnt(6)
	v_mfma_f32_16x16x32_bf16 v[54:57], v[98:101], v[242:245], v[54:57]
	ds_read_b128 v[238:241], v214 offset:25536
	v_pk_mul_f32 v[64:65], v[148:149], v[64:65]
	s_waitcnt lgkmcnt(6)
	v_mfma_f32_16x16x32_bf16 v[54:57], v[102:105], v[248:251], v[54:57]
	ds_read_b128 v[242:245], v214 offset:25600
	s_waitcnt lgkmcnt(6)
	v_mfma_f32_16x16x32_bf16 v[54:57], v[106:109], v[252:255], v[54:57]
	ds_read_b128 v[248:251], v214 offset:25664
	s_waitcnt lgkmcnt(6)
	v_mfma_f32_16x16x32_bf16 v[54:57], v[110:113], v[222:225], v[54:57]
	ds_read_b128 v[252:255], v214 offset:25728
	s_waitcnt lgkmcnt(6)
	v_mfma_f32_16x16x32_bf16 v[50:53], v[82:85], v[226:229], 0
	ds_read_b128 v[222:225], v214 offset:25792
	s_waitcnt lgkmcnt(6)
	v_mfma_f32_16x16x32_bf16 v[50:53], v[86:89], v[230:233], v[50:53]
	s_waitcnt lgkmcnt(5)
	v_mfma_f32_16x16x32_bf16 v[50:53], v[90:93], v[234:237], v[50:53]
	v_pk_mul_f32 v[58:59], v[144:145], v[58:59]
	s_waitcnt lgkmcnt(4)
	v_mfma_f32_16x16x32_bf16 v[50:53], v[94:97], v[238:241], v[50:53]
	s_waitcnt lgkmcnt(3)
	v_mfma_f32_16x16x32_bf16 v[50:53], v[98:101], v[242:245], v[50:53]
	v_pk_mul_f32 v[60:61], v[148:149], v[60:61]
	s_waitcnt lgkmcnt(2)
	v_mfma_f32_16x16x32_bf16 v[50:53], v[102:105], v[248:251], v[50:53]
	s_waitcnt lgkmcnt(1)
	v_mfma_f32_16x16x32_bf16 v[50:53], v[106:109], v[252:255], v[50:53]
	s_waitcnt lgkmcnt(0)
	v_mfma_f32_16x16x32_bf16 v[50:53], v[110:113], v[222:225], v[50:53]
	v_pk_mul_f32 v[54:55], v[144:145], v[54:55]
	v_pk_mul_f32 v[56:57], v[148:149], v[56:57]
	s_nop 5
	v_pk_mul_f32 v[50:51], v[144:145], v[50:51]
	v_pk_mul_f32 v[52:53], v[148:149], v[52:53]
	s_branch .LBB0_1049
